# v105 stack with the scan-phase raise on waves 0-3 instead of 4-7
# baseline (speedup 1.0000x reference)
; __device__ __forceinline__ void ssd_phase(const Args& A, unsigned char* smem, const bool dry) {
;     ...
;     for (int u = blockIdx.x; u < 256; u += gridDim.x) {
;         const int b = u >> 4, h = u & 15, g = h >> 2;
;         __syncthreads();
;         const float Dh = A.in[6][h];
;         for (int dir = 0; dir < 2; ++dir) {
;             const float a_neg = -__expf(A.in[4][dir * 16 + h]); const float dtb = A.in[5][dir * 16 + h];
;             f32x4 Sacc[4];
; #pragma unroll
;             for (int j = 0; j < 4; ++j) Sacc[j] = (f32x4){0.f, 0.f, 0.f, 0.f};
;             __syncthreads();
;             for (int e = tid; e < 64 * 136 / 2; e += 512) ((unsigned*)Sb)[e] = 0u;
;             u32x4 pre[5]; float dpre = 0.f;
;     ...
;             SSD_ISSUE(0);
.LBB0_414:
	s_add_i32 s36, s36, s41
	s_mov_b32 s92, s41
	s_cmpk_gt_i32 s36, 0xff
	s_cbranch_scc1 .LBB0_482
.LBB0_415:
	s_setprio 0
	v_readfirstlane_b32 s98, v152
	s_nop 3
	s_cmp_lt_u32 s98, 0x100
	s_cbranch_scc0 .Lsp0_skip
	s_setprio 1
.Lsp0_skip:
	s_and_b32 s37, s36, 15
	s_lshl_b32 s6, s37, 2
	v_readlane_b32 s76, v251, 4
	s_waitcnt vmcnt(4)
	v_mov_b32_e32 v0, s6
	v_readlane_b32 s88, v251, 16
	v_readlane_b32 s89, v251, 17
	s_barrier
	s_lshl_b32 s7, s36, 8
	s_lshl_b32 s10, s36, 5
	s_nop 1
	global_load_dword v54, v0, s[88:89]
	s_and_b32 s40, s7, 0xfffff000
	s_and_b32 s7, s10, 0x180
	s_lshl_b32 s14, s37, 6
	s_add_i32 s10, s7, 0x540
	s_addk_i32 s7, 0x3c0
	v_readlane_b32 s18, v251, 52
	s_add_u32 s44, s18, s6
	s_waitcnt vmcnt(4)
	v_mov_b32_e32 v6, s7
	v_readlane_b32 s6, v250, 3
	v_mov_b32_e32 v5, s10
	v_readlane_b32 s7, v250, 4
	v_readlane_b32 s19, v251, 53
	s_mov_b32 s11, s94
	v_cndmask_b32_e64 v7, v5, v6, s[6:7]
	v_readlane_b32 s6, v250, 7
	v_readlane_b32 s7, v250, 8
	s_addc_u32 s45, s19, 0
	s_lshl_b32 s10, s37, 7
	s_waitcnt vmcnt(3)
	v_cndmask_b32_e64 v8, v5, v6, s[6:7]
	v_readlane_b32 s6, v250, 11
	v_readlane_b32 s7, v250, 12
	v_lshl_add_u64 v[56:57], v[48:49], 0, s[10:11]
	v_readlane_b32 s10, v250, 1
	v_cndmask_b32_e64 v9, v5, v6, s[6:7]
	v_readlane_b32 s6, v250, 15
	v_readlane_b32 s7, v250, 16
	v_or_b32_e32 v0, s14, v102
	v_readlane_b32 s11, v250, 2
	v_cndmask_b32_e64 v10, v5, v6, s[6:7]
	v_readlane_b32 s6, v250, 19
	v_readlane_b32 s7, v250, 20
	v_or_b32_e32 v1, s14, v105
	v_or_b32_e32 v2, s14, v108
	v_cndmask_b32_e64 v5, v5, v6, s[6:7]
	v_add_u32_e32 v6, v7, v102
	v_cndmask_b32_e64 v0, v6, v0, s[10:11]
	v_readlane_b32 s10, v250, 5
	v_add_u32_e32 v7, v8, v105
	v_readlane_b32 s11, v250, 6
	v_add_u32_e32 v8, v9, v108
	v_lshlrev_b32_e32 v46, 1, v0
	v_cndmask_b32_e64 v1, v7, v1, s[10:11]
	v_readlane_b32 s10, v250, 9
	v_readlane_b32 s11, v250, 10
	v_or_b32_e32 v3, s14, v111
	v_add_u32_e32 v9, v10, v111
	v_cndmask_b32_e64 v2, v8, v2, s[10:11]
	v_readlane_b32 s10, v250, 13
	v_readlane_b32 s11, v250, 14
	v_lshl_add_u64 v[58:59], s[96:97], 0, v[46:47]
	v_lshlrev_b32_e32 v46, 1, v1
	v_cndmask_b32_e64 v3, v9, v3, s[10:11]
	v_lshl_add_u64 v[60:61], s[96:97], 0, v[46:47]
	v_lshlrev_b32_e32 v46, 1, v2
	v_readlane_b32 s10, v250, 17
	v_or_b32_e32 v4, s14, v114
	v_add_u32_e32 v5, v5, v114
	v_lshl_add_u64 v[62:63], s[96:97], 0, v[46:47]
	v_lshlrev_b32_e32 v46, 1, v3
	v_readlane_b32 s11, v250, 18
	v_lshl_add_u64 v[64:65], s[96:97], 0, v[46:47]
	s_mov_b32 s41, s92
	v_cndmask_b32_e64 v46, v5, v4, s[10:11]
	s_mov_b64 s[92:93], -1
	s_lshl_b32 s6, s14, 1
	v_lshl_add_u64 v[66:67], v[46:47], 1, s[96:97]
	s_mov_b32 s14, s94
	v_readlane_b32 s77, v251, 5
	v_readlane_b32 s78, v251, 6
	v_readlane_b32 s79, v251, 7
	v_readlane_b32 s80, v251, 8
	v_readlane_b32 s81, v251, 9
	v_readlane_b32 s82, v251, 10
	v_readlane_b32 s83, v251, 11
	v_readlane_b32 s84, v251, 12
	v_readlane_b32 s85, v251, 13
	v_readlane_b32 s86, v251, 14
	v_readlane_b32 s87, v251, 15
	v_readlane_b32 s90, v251, 18
	s_waitcnt vmcnt(0)
	v_mov_b32_e32 v55, v54
	v_readlane_b32 s91, v251, 19
	s_branch .LBB0_417

; __device__ __forceinline__ u16 f2bf(float f) { unsigned u = __float_as_uint(f); u += 0x7FFFu + ((u >> 16) & 1u); return (u16)(u >> 16); }
; #define LRU_ISSUE(BT) do { _Pragma("unroll") for (int k = 0; k < 2; ++k) { const int i_ = si + 64 * k; const int t_ = dir ? (SEQ - 1 - ((BT) * 128 + i_)) : ((BT) * 128 + i_); \
;         lpre[k] = *(const u32x4*)(proj + (size_t)(b * SEQ + t_) * PLD + 2048 + 64 * nb + c8); } } while (0)
; __device__ __forceinline__ void lru_phase(const Args& A, unsigned char* smem, const bool dry) {
;     ...
;     for (int u = blockIdx.x; u < 256; u += gridDim.x) {
;         const int b = u >> 4, nb = u & 15;
;         for (int dir = 0; dir < 2; ++dir) {
;             __syncthreads();
;             for (int e = tid; e < 8192; e += 512) { const int gate = e >> 12, c = (e >> 6) & 63, d = e & 63;
;                 const float v = (gate ? A.in[10] : A.in[8])[(size_t)((dir * 16 + nb) * 64 + c) * 64 + d]; wT[(gate * 64 + d) * 72 + c] = f2bf(v); }
;             if (tid < 64) hcar[tid] = 0.f;
;             float ba[4], bx[4], sp[4];
; #pragma unroll
;             for (int dt = 0; dt < 4; ++dt) { const int ch = dir * 1024 + 64 * nb + 16 * dt + r16; ba[dt] = A.in[9][ch]; bx[dt] = A.in[11][ch];
;                 const float ml = -A.in[12][ch]; sp[dt] = ml > 20.f ? ml : log1pf(__expf(ml)); }
;             u32x4 lpre[2];
;     ...
;             LRU_ISSUE(0);
.LBB0_485:
	s_add_i32 s45, s45, s92
	s_cmpk_gt_i32 s45, 0xff
	s_cbranch_scc1 .LBB0_557
.LBB0_486:
	s_setprio 0
	v_readfirstlane_b32 s98, v152
	s_nop 3
	s_cmp_lt_u32 s98, 0x100
	s_cbranch_scc0 .Lsp1_skip
	s_setprio 1
.Lsp1_skip:
	s_lshl_b32 s8, s45, 6
	s_and_b32 s46, s8, 0x3c0
	s_lshl_b32 s8, s45, 8
	s_and_b32 s47, s8, 0xfffff000
	s_waitcnt vmcnt(1)
	v_bitop3_b32 v0, s47, v138, v65 bitop3:0x36
	s_lshl_b32 s12, s46, 1
	v_lshl_add_u64 v[50:51], v[44:45], 0, s[12:13]
	v_sub_u32_e32 v143, v0, v74
	v_sub_u32_e32 v144, v0, v75
	s_mov_b64 s[16:17], -1
	s_mov_b32 s8, s13
	s_branch .LBB0_488

; __device__ __forceinline__ float sigmoidf_(float x) { return __builtin_amdgcn_rcpf(1.0f + __expf(-x)); }
; __device__ __forceinline__ void hgrn_phase(const Args& A, unsigned char* smem, const bool dry) {
;     ...
;     for (int u = blockIdx.x; u < 256; u += gridDim.x) {
;         const int b = u >> 4, dir = (u >> 3) & 1, h = u & 7;
;         float lbk[4];
; #pragma unroll
;         for (int c = 0; c < 4; ++c) lbk[c] = sigmoidf_(A.in[15][1024 + 128 * h + 4 * cq + c] - A.in[15][128 * h + 4 * cq + c]);
.LBB0_980:
	s_add_i32 s85, s85, s92
	s_cmpk_gt_i32 s85, 0xff
	s_cbranch_scc1 .LBB0_991
.LBB0_981:
	s_setprio 0
	v_readfirstlane_b32 s98, v152
	s_nop 3
	s_cmp_lt_u32 s98, 0x100
	s_cbranch_scc0 .Lsp2_skip
	s_setprio 1
.Lsp2_skip:
	s_lshl_b32 s52, s85, 7
	s_and_b32 s72, s52, 0x380
	v_or_b32_e32 v0, s72, v113
	v_readlane_b32 s56, v251, 20
	v_lshlrev_b32_e32 v4, 2, v0
	v_mov_b32_e32 v5, v81
	v_readlane_b32 s70, v251, 34
	v_readlane_b32 s71, v251, 35
	s_mov_b64 s[52:53], 0
	v_readlane_b32 s57, v251, 21
	v_lshl_add_u64 v[0:1], s[70:71], 0, v[4:5]
	v_add_co_u32_e32 v0, vcc, 0x1000, v0
	v_readlane_b32 s58, v251, 22
	s_nop 0
	v_addc_co_u32_e32 v1, vcc, 0, v1, vcc
	global_load_dwordx4 v[0:3], v[0:1], off
	s_nop 0
	global_load_dwordx4 v[4:7], v4, s[70:71]
	v_readlane_b32 s59, v251, 23
	v_readlane_b32 s60, v251, 24
	v_readlane_b32 s61, v251, 25
	v_readlane_b32 s62, v251, 26
	v_readlane_b32 s63, v251, 27
	v_readlane_b32 s64, v251, 28
	v_readlane_b32 s65, v251, 29
	v_readlane_b32 s66, v251, 30
	v_readlane_b32 s67, v251, 31
	v_readlane_b32 s68, v251, 32
	v_readlane_b32 s69, v251, 33
	s_barrier
	s_waitcnt vmcnt(0)
	v_sub_f32_e32 v0, v0, v4
	v_sub_f32_e32 v1, v1, v5
	v_sub_f32_e32 v2, v2, v6
	v_sub_f32_e32 v3, v3, v7
	v_mul_f32_e32 v0, 0xbfb8aa3b, v0
	v_mul_f32_e32 v1, 0xbfb8aa3b, v1
	v_mul_f32_e32 v2, 0xbfb8aa3b, v2
	v_mul_f32_e32 v3, 0xbfb8aa3b, v3
	v_exp_f32_e32 v0, v0
	v_exp_f32_e32 v1, v1
	v_exp_f32_e32 v2, v2
	v_exp_f32_e32 v3, v3
	v_mov_b32_e32 v4, v136
	v_mov_b32_e32 v5, v135
